# hardened: remap+fast path only when gridDim==256 and blockIdx%8-XCC check passes, else original global barriers
# speedup vs baseline: 1.0169x; 1.0014x over previous
.LBB0_124:
	s_or_b64 exec, exec, s[38:39]
	s_mov_b64 s[4:5], s[0:1]
	s_waitcnt lgkmcnt(0)
	s_barrier
	s_load_dwordx2 s[98:99], s[0:1], 0xd8
	v_mov_b32_e32 v10, 0
	v_mov_b32_e32 v11, 0
	s_waitcnt lgkmcnt(0)
	global_load_dwordx4 v[0:3], v10, s[98:99] offset:64 sc1
	global_load_dwordx4 v[4:7], v10, s[98:99] offset:80 sc1
	s_waitcnt vmcnt(0)
	v_or3_b32 v8, v0, v1, v2
	v_or3_b32 v8, v8, v3, v4
	v_or3_b32 v8, v8, v5, v6
	v_or_b32_e32 v8, v8, v7
	v_add_u32_e32 v9, -1, v0
	v_and_b32_e32 v9, v9, v0
	v_or_b32_e32 v11, v11, v9
	v_add_u32_e32 v9, -1, v1
	v_and_b32_e32 v9, v9, v1
	v_or_b32_e32 v11, v11, v9
	v_add_u32_e32 v9, -1, v2
	v_and_b32_e32 v9, v9, v2
	v_or_b32_e32 v11, v11, v9
	v_add_u32_e32 v9, -1, v3
	v_and_b32_e32 v9, v9, v3
	v_or_b32_e32 v11, v11, v9
	v_add_u32_e32 v9, -1, v4
	v_and_b32_e32 v9, v9, v4
	v_or_b32_e32 v11, v11, v9
	v_add_u32_e32 v9, -1, v5
	v_and_b32_e32 v9, v9, v5
	v_or_b32_e32 v11, v11, v9
	v_add_u32_e32 v9, -1, v6
	v_and_b32_e32 v9, v9, v6
	v_or_b32_e32 v11, v11, v9
	v_add_u32_e32 v9, -1, v7
	v_and_b32_e32 v9, v9, v7
	v_or_b32_e32 v11, v11, v9
	v_xor_b32_e32 v8, 0xff, v8
	v_or_b32_e32 v8, v8, v11
	s_nop 0
	v_readfirstlane_b32 s98, v8
	s_cmp_eq_u32 s98, 0
	s_cselect_b32 s98, 1, 0
	s_cmp_eq_u32 s68, 0x100
	s_cselect_b32 s98, s98, 0
	v_writelane_b32 v254, s98, 2
	s_cmpk_lt_i32 s2, 0x200
	v_mov_b64_e32 v[0:1], s[4:5]
	flat_load_dwordx2 v[0:1], v[0:1] offset:216
	v_mov_b32_e32 v10, v176
	s_cselect_b64 s[46:47], -1, 0
	s_and_b64 vcc, exec, s[46:47]
	v_readfirstlane_b32 s6, v10
	s_cbranch_vccz .LBB0_130
	s_lshr_b32 s3, s33, 29
	s_add_i32 s3, s2, s3
	s_and_b32 s4, s3, -8
	s_sub_i32 s7, s2, s4
	s_cmp_gt_i32 s7, -1
	s_cbranch_scc0 .LBB0_127
	s_lshl_b32 s8, s7, 6
	s_cbranch_execz .LBB0_128
	s_branch .LBB0_129

.LBB0_312:
	s_or_b64 exec, exec, s[50:51]
	v_mov_b32_e32 v0, v176
	s_cmp_eq_u32 s68, 0x100
	s_cbranch_scc0 .Lrm_orig_lru_9673
	s_and_b32 s3, s2, 7
	s_lshl_b32 s3, s3, 5
	s_lshr_b32 s98, s2, 3
	s_add_i32 s3, s3, s98
	s_branch .Lrm_done_lru_9673
.Lrm_orig_lru_9673:
	s_mov_b32 s3, s2
.Lrm_done_lru_9673:
	s_mov_b32 s10, s68
	s_waitcnt lgkmcnt(0)
	s_barrier
	s_lshl_b32 s3, s3, 3
	v_readfirstlane_b32 s6, v0
	s_ashr_i32 s7, s6, 6
	s_add_i32 s3, s3, s7
	s_mov_b64 s[8:9], s[0:1]
	s_cmpk_gt_i32 s3, 0x7ff
	s_cbranch_scc1 .LBB0_321
	v_bfe_u32 v3, v0, 4, 2
	s_mulk_i32 s7, 0x4400
	v_lshlrev_b32_e32 v77, 2, v3
	v_and_b32_e32 v1, 63, v0
	s_add_i32 s7, s7, 0
	v_and_b32_e32 v72, 15, v0
	v_and_b32_e32 v0, 48, v0
	v_or_b32_e32 v102, 1, v77
	v_or_b32_e32 v104, 2, v77
	v_or_b32_e32 v106, 3, v77
	v_lshlrev_b32_e32 v2, 9, v3
	v_add_u32_e32 v76, s7, v0
	v_lshl_add_u32 v0, v3, 11, s7
	v_lshlrev_b32_e32 v3, 3, v72
	v_lshl_add_u32 v4, v102, 9, s7
	v_lshl_add_u32 v5, v104, 9, s7
	v_lshl_add_u32 v6, v106, 9, s7
	v_add_u32_e32 v79, v0, v3
	v_add_u32_e32 v103, v4, v3
	v_add_u32_e32 v105, v5, v3
	v_add_u32_e32 v107, v6, v3
	v_or_b32_e32 v7, 0x80, v3
	v_or_b32_e32 v3, 0x100, v3
	s_bfe_u32 s6, s6, 0x20006
	s_lshl_b32 s20, s10, 3
	v_add_u32_e32 v112, v0, v3
	v_add_u32_e32 v113, v4, v3
	v_add_u32_e32 v114, v5, v3
	v_add_u32_e32 v115, v6, v3
	v_or_b32_e32 v3, 48, v1
	s_lshl_b32 s10, s6, 6
	v_lshl_add_u32 v73, v1, 1, s7
	v_add_u32_e32 v108, v0, v7
	v_add_u32_e32 v109, v4, v7
	v_add_u32_e32 v110, v5, v7
	v_add_u32_e32 v111, v6, v7
	v_lshlrev_b32_e32 v7, 3, v3
	v_or_b32_e32 v78, s10, v1
	v_lshl_add_u32 v1, v1, 3, s7
	v_mov_b32_e32 v75, 0
	v_add_u32_e32 v116, v0, v7
	s_lshl_b32 s6, s6, 12
	v_or_b32_e32 v0, s10, v72
	v_add_u32_e32 v122, 0x2400, v1
	v_mov_b32_e32 v1, 0x18000800
	s_mov_b32 s11, 0
	v_add_u32_e32 v117, v4, v7
	v_add_u32_e32 v118, v5, v7
	v_add_u32_e32 v119, v6, v7
	v_lshl_add_u32 v120, v72, 1, s7
	v_lshl_add_u32 v121, v3, 1, s7
	v_lshlrev_b32_e32 v80, 3, v78
	v_mov_b32_e32 v81, v75
	v_lshl_or_b32 v82, v78, 2, v1
	v_mov_b32_e32 v83, v75
	v_mov_b64_e32 v[84:85], s[8:9]
	v_lshlrev_b32_e32 v86, 2, v78
	v_mov_b32_e32 v87, v75
	s_and_b32 s12, s2, 7
	s_lshl_b32 s12, s12, 23
	s_add_u32 s12, s12, 0xd000000
	s_mov_b32 s13, 0
	s_lshl_b32 s10, s6, 2
	v_lshlrev_b32_e32 v88, 2, v2
	v_lshlrev_b32_e32 v90, 2, v72
	s_movk_i32 s21, 0x2000
	s_movk_i32 s22, 0x1000
	s_movk_i32 s23, 0x3000
	s_movk_i32 s26, 0x4000
	s_movk_i32 s27, 0x5000
	s_movk_i32 s28, 0x6000
	s_movk_i32 s29, 0x7000
	s_mov_b32 s30, 0x8000
	s_mov_b32 s31, 0x9000
	s_mov_b32 s34, 0xa000
	s_mov_b32 s35, 0xb000
	s_mov_b32 s36, 0xc000
	s_mov_b32 s37, 0xd000
	s_mov_b32 s38, 0xe000
	s_mov_b32 s39, 0xf000
	s_mov_b32 s42, 0x10000
	s_mov_b32 s43, 0x11000
	s_mov_b32 s44, 0x12000
	s_mov_b32 s45, 0x13000
	s_mov_b32 s50, 0x14000
	s_mov_b32 s51, 0x15000
	s_mov_b32 s52, 0x16000
	s_mov_b32 s53, 0x17000
	s_mov_b32 s54, 0x18000
	s_mov_b32 s55, 0x19000
	s_mov_b32 s56, 0x1a000
	s_mov_b32 s57, 0x1b000
	s_mov_b32 s58, 0x1c000
	s_mov_b32 s59, 0x1d000
	s_mov_b32 s60, 0x1e000
	s_mov_b32 s61, 0x1f000
	s_mov_b32 s62, 0x20000
	s_mov_b32 s63, 0x21000
	s_mov_b32 s64, 0x22000
	s_mov_b32 s65, 0x23000
	s_mov_b32 s66, 0x24000
	s_mov_b32 s67, 0x25000
	s_mov_b32 s70, 0x26000
	s_mov_b32 s71, 0x27000
	s_mov_b32 s72, 0x28000
	s_mov_b32 s73, 0x29000
	s_mov_b32 s74, 0x2a000
	s_mov_b32 s75, 0x2b000
	s_mov_b32 s76, 0x2c000
	s_mov_b32 s77, 0x2d000
	s_mov_b32 s78, 0x2e000
	s_mov_b32 s79, 0x2f000
	s_mov_b32 s80, 0x30000
	s_mov_b32 s81, 0x31000
	s_mov_b32 s82, 0x32000
	s_mov_b32 s83, 0x33000
	s_mov_b32 s84, 0x34000
	s_mov_b32 s85, 0x35000
	s_mov_b32 s86, 0x36000
	s_mov_b32 s87, 0x37000
	v_lshlrev_b32_e32 v92, 2, v0
	s_mov_b32 s88, 0x3f2aaaab
	v_mov_b32_e32 v123, 0x3ecc95a3
	s_mov_b32 s89, 0x3f317218
	s_mov_b32 s90, 0x7f800000
	s_mov_b32 s91, 0x33800000
	s_movk_i32 s92, 0x90
	s_mov_b32 s93, 0xf800000
	v_mov_b32_e32 v124, 0x260
	s_mov_b64 s[14:15], 0x1000
	s_mov_b64 s[16:17], 0x4000
	v_mov_b32_e32 v125, 0xe00
	v_mov_b32_e32 v126, 0x7f800000
	v_mov_b32_e32 v127, 0x7fc00000
	v_mov_b32_e32 v128, 0xff800000

.LBB0_321:
	v_mov_b32_e32 v0, v176
	s_cmp_eq_u32 s68, 0x100
	s_cbranch_scc0 .Lrm_orig_attn_12323
	s_and_b32 s3, s2, 7
	s_lshl_b32 s3, s3, 6
	s_lshr_b32 s98, s2, 3
	s_add_i32 s3, s3, s98
	s_add_i32 s99, s3, 32
	s_mov_b32 s42, 32
	s_branch .Lrm_done_attn_12323
.Lrm_orig_attn_12323:
	s_mov_b32 s3, s2
	s_mov_b32 s42, s68
	s_movk_i32 s99, 0x1ff
.Lrm_done_attn_12323:
	s_mov_b64 s[22:23], s[0:1]
	s_barrier
	s_load_dwordx2 s[86:87], s[0:1], 0xe0
	v_readfirstlane_b32 s6, v0
	s_cmpk_gt_i32 s3, 0x1ff
	v_mbcnt_lo_u32_b32 v216, -1, 0
	s_cbranch_scc1 .LBB0_334
	v_mbcnt_hi_u32_b32 v10, -1, v216
	v_and_b32_e32 v12, 64, v10
	v_xor_b32_e32 v11, 16, v10
	v_add_u32_e32 v12, 64, v12
	v_cmp_lt_i32_e32 vcc, v11, v12
	v_and_b32_e32 v1, 7, v0
	v_add_u32_e32 v6, 0x400, v0
	v_cndmask_b32_e32 v11, v10, v11, vcc
	s_ashr_i32 s26, s6, 6
	v_lshl_add_u32 v3, v1, 4, 0
	s_movk_i32 s6, 0x1070
	v_add_u32_e32 v5, 0x200, v0
	v_ashrrev_i32_e32 v90, 3, v6
	v_add_u32_e32 v6, 0x600, v0
	v_lshlrev_b32_e32 v111, 2, v11
	v_xor_b32_e32 v11, 32, v10
	v_mad_u32_u24 v4, v1, s6, v3
	v_ashrrev_i32_e32 v86, 3, v0
	v_ashrrev_i32_e32 v88, 3, v5
	v_ashrrev_i32_e32 v92, 3, v6
	v_bfe_u32 v6, v0, 4, 2
	v_cmp_lt_i32_e32 vcc, v11, v12
	v_lshl_add_u32 v85, v86, 1, v4
	v_lshl_add_u32 v108, v88, 1, v4
	v_lshl_add_u32 v109, v90, 1, v4
	v_lshl_add_u32 v110, v92, 1, v4
	v_lshlrev_b32_e32 v4, 3, v6
	v_lshlrev_b32_e32 v6, 2, v6
	v_cndmask_b32_e32 v10, v10, v11, vcc
	s_and_b32 s43, s26, 3
	s_lshl_b32 s14, s26, 4
	v_and_b32_e32 v9, 15, v0
	v_lshlrev_b32_e32 v112, 2, v10
	v_or_b32_e32 v10, 2, v6
	s_lshr_b32 s26, s26, 2
	v_cmp_gt_u32_e64 s[18:19], v10, v9
	v_or_b32_e32 v10, 3, v6
	s_lshl_b32 s29, s26, 7
	v_cmp_gt_u32_e64 s[20:21], v10, v9
	v_and_or_b32 v10, v0, 63, 48
	s_movk_i32 s30, 0x210
	v_mov_b32_e32 v11, s29
	v_mad_u32_u24 v10, v10, s30, v11
	v_add3_u32 v10, v10, v4, 0
	v_add_u32_e32 v113, 0x9000, v10
	v_mad_u32_u24 v10, v9, s30, v11
	v_add3_u32 v10, v10, v4, 0
	s_lshl_b32 s44, s26, 6
	s_mulk_i32 s26, 0x2400
	s_movk_i32 s28, 0x90
	s_andn2_b32 s14, s14, 63
	v_add_u32_e32 v114, 0x9000, v10
	v_mov_b32_e32 v10, s26
	v_lshlrev_b32_e32 v84, 3, v1
	s_movk_i32 s12, 0x7f
	v_mul_lo_u32 v1, v86, s28
	v_mul_lo_u32 v5, v88, s28
	v_mul_lo_u32 v7, v90, s28
	v_mul_lo_u32 v8, v92, s28
	s_ashr_i32 s15, s14, 31
	v_mad_u32_u24 v10, v9, s28, v10
	v_and_b32_e32 v0, 48, v0
	s_mov_b32 s27, 0
	v_mov_b32_e32 v2, 0
	v_cmp_lt_i32_e64 s[6:7], s12, v86
	v_ashrrev_i32_e32 v87, 31, v86
	v_cmp_lt_i32_e64 s[8:9], s12, v88
	v_ashrrev_i32_e32 v89, 31, v88
	v_cmp_lt_i32_e64 s[10:11], s12, v90
	v_ashrrev_i32_e32 v91, 31, v90
	v_cmp_lt_i32_e64 s[12:13], s12, v92
	v_ashrrev_i32_e32 v93, 31, v92
	v_or_b32_e32 v94, s14, v9
	v_mov_b32_e32 v95, s15
	v_cmp_gt_u32_e64 s[14:15], v6, v9
	v_cmp_lt_u32_e64 s[16:17], v6, v9
	v_add3_u32 v115, v10, v0, 0
	v_or_b32_e32 v116, s44, v9
	v_mov_b64_e32 v[96:97], s[22:23]
	s_and_b32 s28, s2, 7
	s_lshl_b32 s28, s28, 23
	s_add_u32 s28, s28, 0xd000000
	s_mov_b32 s29, 0
	s_movk_i32 s45, 0xe00
	v_add_u32_e32 v117, v3, v1
	v_add_u32_e32 v118, v3, v5
	v_add_u32_e32 v119, v3, v7
	v_add_u32_e32 v120, v3, v8
	v_lshlrev_b32_e32 v98, 1, v4
	s_mov_b32 s50, 0xf149f2ca
	v_lshlrev_b32_e32 v100, 1, v6
	s_mov_b64 s[30:31], 0x9000200
	s_mov_b32 s51, 0x9000000
	v_mov_b32_e32 v121, 0xf149f2ca

.LBB0_334:
	v_mov_b32_e32 v54, v176
	s_cmp_eq_u32 s68, 0x100
	s_cbranch_scc0 .Lrm_orig_conf_13188
	s_and_b32 s27, s2, 7
	s_lshl_b32 s27, s27, 7
	s_lshr_b32 s98, s2, 3
	s_add_i32 s27, s27, s98
	s_add_i32 s99, s27, 96
	s_mov_b32 s3, 32
	s_branch .Lrm_done_conf_13188
.Lrm_orig_conf_13188:
	s_mov_b32 s27, s2
	s_mov_b32 s3, s68
	s_movk_i32 s99, 0x3ff
.Lrm_done_conf_13188:
	s_mov_b64 s[6:7], s[0:1]
	v_readfirstlane_b32 s18, v54
	s_cmpk_gt_i32 s27, 0x3ff
	s_cbranch_scc1 .LBB0_367
	v_mov_b64_e32 v[0:1], s[6:7]
	flat_load_dwordx4 v[2:5], v[0:1] offset:120
	flat_load_dwordx4 v[6:9], v[0:1] offset:136
	flat_load_dwordx2 v[40:41], v[0:1] offset:216
	flat_load_dwordx2 v[12:13], v[0:1] offset:152
	v_and_b32_e32 v55, 0xff, v54
	v_mov_b32_e32 v0, 0
	v_and_b32_e32 v56, 63, v54
	v_lshlrev_b32_e32 v10, 2, v55
	v_mov_b32_e32 v11, v0
	s_movk_i32 s6, 0x1000
	v_lshlrev_b32_e32 v14, 4, v56
	v_mov_b32_e32 v15, v0
	s_movk_i32 s7, 0x2000
	s_movk_i32 s8, 0x3000
	s_movk_i32 s9, 0x4000
	s_movk_i32 s10, 0x5000
	s_movk_i32 s11, 0x6000
	s_movk_i32 s12, 0x7000
	s_lshl_b32 s20, s27, 5
	v_ashrrev_i32_e32 v90, 5, v54
	v_lshlrev_b32_e32 v57, 3, v54
	v_and_b32_e32 v94, 0xf8, v57
	v_mov_b32_e32 v1, v0
	v_lshlrev_b32_e32 v52, 1, v94
	s_waitcnt vmcnt(0) lgkmcnt(0)
	v_lshl_add_u64 v[2:3], v[2:3], 0, v[10:11]
	v_lshl_add_u64 v[18:19], v[8:9], 0, v[14:15]
	v_add_co_u32_e32 v8, vcc, s6, v2
	v_lshl_add_u64 v[10:11], v[4:5], 0, v[10:11]
	s_nop 0
	v_addc_co_u32_e32 v9, vcc, 0, v3, vcc
	v_add_co_u32_e32 v20, vcc, s7, v2
	v_lshl_add_u64 v[16:17], v[6:7], 0, v[14:15]
	s_nop 0
	v_addc_co_u32_e32 v21, vcc, 0, v3, vcc
	v_add_co_u32_e32 v22, vcc, s8, v2
	s_and_b32 s6, s2, 7
	s_lshl_b32 s6, s6, 23
	s_add_u32 s6, s6, 0xd000000
	s_mov_b32 s7, 0
	s_nop 0
	v_addc_co_u32_e32 v23, vcc, 0, v3, vcc
	v_add_co_u32_e32 v24, vcc, s9, v2
	v_lshl_add_u64 v[50:51], v[40:41], 0, s[6:7]
	s_nop 0
	v_addc_co_u32_e32 v25, vcc, 0, v3, vcc
	v_add_co_u32_e32 v26, vcc, s10, v2
	s_ashr_i32 s6, s27, 7
	s_nop 0
	v_addc_co_u32_e32 v27, vcc, 0, v3, vcc
	v_add_co_u32_e32 v28, vcc, s11, v2
	s_and_b32 s7, s20, 0xfe0
	s_nop 0
	v_addc_co_u32_e32 v29, vcc, 0, v3, vcc
	v_add_co_u32_e32 v30, vcc, s12, v2
	s_sub_i32 s16, s7, 30
	s_nop 0
	v_addc_co_u32_e32 v31, vcc, 0, v3, vcc
	global_load_dword v58, v[10:11], off
	global_load_dwordx4 v[4:7], v[16:17], off
	global_load_dword v59, v[2:3], off
	global_load_dword v60, v[2:3], off offset:1024
	global_load_dword v61, v[2:3], off offset:2048
	global_load_dword v62, v[2:3], off offset:3072
	global_load_dword v63, v[8:9], off offset:1024
	global_load_dword v64, v[8:9], off offset:2048
	global_load_dword v65, v[8:9], off offset:3072
	global_load_dword v66, v[22:23], off offset:1024
	global_load_dword v67, v[20:21], off offset:-4096
	global_load_dword v68, v[20:21], off
	global_load_dword v69, v[20:21], off offset:1024
	global_load_dword v70, v[20:21], off offset:2048
	global_load_dword v71, v[20:21], off offset:3072
	global_load_dword v72, v[24:25], off offset:-4096
	global_load_dword v73, v[24:25], off
	global_load_dword v74, v[24:25], off offset:1024
	global_load_dword v75, v[24:25], off offset:2048
	global_load_dword v76, v[24:25], off offset:3072
	global_load_dword v77, v[28:29], off offset:-4096
	global_load_dword v78, v[28:29], off
	global_load_dword v79, v[28:29], off offset:1024
	global_load_dword v80, v[28:29], off offset:2048
	global_load_dword v81, v[28:29], off offset:3072
	global_load_dword v82, v[22:23], off offset:2048
	global_load_dword v83, v[22:23], off offset:3072
	global_load_dword v84, v[26:27], off offset:1024
	global_load_dword v85, v[26:27], off offset:2048
	global_load_dword v86, v[26:27], off offset:3072
	global_load_dword v87, v[30:31], off
	global_load_dword v88, v[30:31], off offset:1024
	global_load_dword v89, v[30:31], off offset:2048
	global_load_dwordx4 v[8:11], v[18:19], off
	v_lshl_add_u64 v[2:3], v[12:13], 0, v[14:15]
	global_load_dwordx4 v[12:15], v[2:3], off offset:3072
	s_ashr_i32 s7, s6, 31
	s_lshl_b64 s[14:15], s[6:7], 12
	v_add_u32_e32 v24, s16, v90
	s_movk_i32 s6, 0x7c0
	v_mov_b32_e32 v2, v0
	v_mov_b32_e32 v3, v0
	v_cmp_gt_i32_e64 s[6:7], s6, v54
	v_cmp_lt_i32_e32 vcc, -1, v24
	v_mov_b64_e32 v[22:23], v[2:3]
	v_mov_b64_e32 v[18:19], v[2:3]
	s_and_b64 s[10:11], s[6:7], vcc
	v_mov_b64_e32 v[20:21], v[0:1]
	v_mov_b64_e32 v[16:17], v[0:1]
	s_and_saveexec_b64 s[8:9], s[10:11]
	s_cbranch_execz .LBB0_337
	v_mov_b32_e32 v25, v0
	v_lshl_add_u64 v[16:17], s[14:15], 0, v[24:25]
	s_movk_i32 s12, 0xe00
	v_mad_u64_u32 v[18:19], s[10:11], v16, s12, v[50:51]
	v_mad_i32_i24 v19, v17, s12, v19
	v_mov_b32_e32 v53, v0
	v_lshl_add_u64 v[24:25], v[18:19], 0, v[52:53]
	global_load_dwordx4 v[16:19], v[24:25], off offset:2560
	global_load_dwordx4 v[20:23], v[24:25], off offset:3072

.LBB0_411:
	s_or_b64 exec, exec, s[50:51]
	s_waitcnt vmcnt(0)
	v_mov_b32_e32 v0, v176
	s_cmp_eq_u32 s68, 0x100
	s_cbranch_scc0 .Lrm_orig_mix2_14932
	s_and_b32 s3, s2, 7
	s_lshl_b32 s3, s3, 6
	s_lshr_b32 s98, s2, 3
	s_add_i32 s3, s3, s98
	s_add_i32 s99, s3, 32
	s_mov_b32 s18, 32
	s_branch .Lrm_done_mix2_14932
.Lrm_orig_mix2_14932:
	s_mov_b32 s3, s2
	s_mov_b32 s18, s68
	s_movk_i32 s99, 0x1ff
.Lrm_done_mix2_14932:
	s_waitcnt lgkmcnt(0)
	s_barrier
	s_mov_b64 s[6:7], s[0:1]
	v_readfirstlane_b32 s8, v0
	s_cmpk_lt_i32 s3, 0x200
	s_cbranch_scc0 .LBB0_445
	s_ashr_i32 s19, s8, 6
	v_and_b32_e32 v0, 63, v0
	s_lshl_b32 s8, s19, 10
	v_mov_b32_e32 v75, 0
	s_add_i32 s8, s8, 0
	v_lshlrev_b32_e32 v1, 4, v0
	v_lshlrev_b32_e32 v2, 1, v0
	s_lshl_b32 s20, s19, 3
	v_lshlrev_b32_e32 v4, 3, v0
	v_lshlrev_b32_e32 v72, 2, v0
	v_lshlrev_b32_e32 v76, 5, v0
	v_mov_b32_e32 v77, v75
	v_add_u32_e32 v73, s8, v1
	v_add_u32_e32 v108, 0, v1
	s_ashr_i32 s21, s20, 31
	v_mov_b64_e32 v[78:79], s[6:7]
	s_mov_b64 s[8:9], 0x1a000000
	s_mov_b64 s[10:11], 0x9000000
	v_lshlrev_b32_e32 v74, 4, v0
	v_lshlrev_b32_e32 v80, 4, v2
	s_mov_b64 s[12:13], 0x18000000
	s_and_b32 s22, s2, 7
	s_lshl_b32 s22, s22, 23
	s_add_u32 s22, s22, 0xd000000
	v_lshlrev_b32_e32 v82, 1, v4
	s_and_b32 s23, s2, 7
	s_lshl_b32 s23, s23, 23
	s_add_u32 s23, s23, 0xd001000
	s_and_b32 s26, s2, 7
	s_lshl_b32 s26, s26, 23
	s_add_u32 s26, s26, 0xd002000
	s_and_b32 s27, s2, 7
	s_lshl_b32 s27, s27, 23
	s_add_u32 s27, s27, 0xd003000
	s_and_b32 s28, s2, 7
	s_lshl_b32 s28, s28, 23
	s_add_u32 s28, s28, 0xd004000
	s_and_b32 s29, s2, 7
	s_lshl_b32 s29, s29, 23
	s_add_u32 s29, s29, 0xd005000
	s_and_b32 s30, s2, 7
	s_lshl_b32 s30, s30, 23
	s_add_u32 s30, s30, 0xd006000
	v_mov_b32_e32 v109, 0x358637bd
	s_mov_b32 s31, 0x800000
	s_movk_i32 s34, 0x1000
	s_movk_i32 s35, 0x2000
	s_movk_i32 s36, 0x3000
	v_mov_b32_e32 v110, 0xe00
	s_branch .LBB0_415

.LBB0_1049:
	s_or_b64 exec, exec, s[48:49]
	v_mov_b32_e32 v0, v176
	s_mov_b32 s12, s68
	s_cmp_eq_u32 s68, 0x100
	s_cbranch_scc0 .Lrm_orig_lru_31452
	s_and_b32 s3, s2, 7
	s_lshl_b32 s3, s3, 5
	s_lshr_b32 s98, s2, 3
	s_add_i32 s3, s3, s98
	s_branch .Lrm_done_lru_31452

.Lrm_done_lru_31452:
	s_waitcnt lgkmcnt(0)
	s_barrier
	s_lshl_b32 s3, s3, 3
	v_readfirstlane_b32 s8, v0
	s_ashr_i32 s9, s8, 6
	s_add_i32 s3, s3, s9
	s_mov_b64 s[10:11], s[0:1]
	s_cmpk_gt_i32 s3, 0x7ff
	s_cbranch_scc1 .LBB0_1058
	v_bfe_u32 v3, v0, 4, 2
	s_mulk_i32 s9, 0x4400
	v_lshlrev_b32_e32 v77, 2, v3
	v_and_b32_e32 v1, 63, v0
	s_add_i32 s9, s9, 0
	v_and_b32_e32 v72, 15, v0
	v_and_b32_e32 v0, 48, v0
	v_or_b32_e32 v102, 1, v77
	v_or_b32_e32 v104, 2, v77
	v_or_b32_e32 v106, 3, v77
	v_lshlrev_b32_e32 v2, 9, v3
	v_add_u32_e32 v76, s9, v0
	v_lshl_add_u32 v0, v3, 11, s9
	v_lshlrev_b32_e32 v3, 3, v72
	v_lshl_add_u32 v4, v102, 9, s9
	v_lshl_add_u32 v5, v104, 9, s9
	v_lshl_add_u32 v6, v106, 9, s9
	v_add_u32_e32 v79, v0, v3
	v_add_u32_e32 v103, v4, v3
	v_add_u32_e32 v105, v5, v3
	v_add_u32_e32 v107, v6, v3
	v_or_b32_e32 v7, 0x80, v3
	v_or_b32_e32 v3, 0x100, v3
	s_bfe_u32 s8, s8, 0x20006
	s_lshl_b32 s26, s12, 3
	v_add_u32_e32 v112, v0, v3
	v_add_u32_e32 v113, v4, v3
	v_add_u32_e32 v114, v5, v3
	v_add_u32_e32 v115, v6, v3
	v_or_b32_e32 v3, 48, v1
	s_lshl_b32 s12, s8, 6
	v_lshl_add_u32 v73, v1, 1, s9
	v_add_u32_e32 v108, v0, v7
	v_add_u32_e32 v109, v4, v7
	v_add_u32_e32 v110, v5, v7
	v_add_u32_e32 v111, v6, v7
	v_lshlrev_b32_e32 v7, 3, v3
	v_or_b32_e32 v78, s12, v1
	v_lshl_add_u32 v1, v1, 3, s9
	v_mov_b32_e32 v75, 0
	v_add_u32_e32 v116, v0, v7
	s_lshl_b32 s8, s8, 12
	v_or_b32_e32 v0, s12, v72
	v_add_u32_e32 v122, 0x2400, v1
	v_mov_b32_e32 v1, 0x18000800
	s_mov_b32 s13, 0
	v_add_u32_e32 v117, v4, v7
	v_add_u32_e32 v118, v5, v7
	v_add_u32_e32 v119, v6, v7
	v_lshl_add_u32 v120, v72, 1, s9
	v_lshl_add_u32 v121, v3, 1, s9
	v_lshlrev_b32_e32 v80, 3, v78
	v_mov_b32_e32 v81, v75
	v_lshl_or_b32 v82, v78, 2, v1
	v_mov_b32_e32 v83, v75
	v_mov_b64_e32 v[84:85], s[10:11]
	v_lshlrev_b32_e32 v86, 2, v78
	v_mov_b32_e32 v87, v75
	s_mov_b64 s[14:15], 0x1000
	s_movk_i32 s27, 0x1000
	s_and_b32 s16, s2, 7
	s_lshl_b32 s16, s16, 23
	s_add_u32 s16, s16, 0xd000000
	s_mov_b32 s17, 0
	s_lshl_b32 s12, s8, 2
	v_lshlrev_b32_e32 v88, 2, v2
	v_lshlrev_b32_e32 v90, 2, v72
	s_mov_b64 s[18:19], 0x10000
	s_mov_b32 s28, 0x10000
	s_mov_b32 s29, 0x12000
	s_movk_i32 s30, 0x2000
	s_movk_i32 s31, 0x3000
	s_movk_i32 s34, 0x4000
	s_movk_i32 s35, 0x5000
	s_movk_i32 s36, 0x6000
	s_movk_i32 s37, 0x7000
	s_mov_b32 s38, 0x8000
	s_mov_b32 s39, 0x9000
	s_mov_b32 s40, 0xa000
	s_mov_b32 s41, 0xb000
	s_mov_b32 s42, 0xc000
	s_mov_b32 s43, 0xd000
	s_mov_b32 s44, 0xe000
	s_mov_b32 s45, 0xf000
	s_mov_b32 s48, 0x11000
	s_mov_b32 s49, 0x13000
	s_mov_b32 s50, 0x14000
	s_mov_b32 s51, 0x15000
	s_mov_b32 s52, 0x16000
	s_mov_b32 s53, 0x17000
	s_mov_b32 s54, 0x18000
	s_mov_b32 s55, 0x19000
	s_mov_b32 s56, 0x1a000
	s_mov_b32 s57, 0x1b000
	s_mov_b32 s58, 0x1c000
	s_mov_b32 s59, 0x1d000
	s_mov_b32 s60, 0x1e000
	s_mov_b32 s61, 0x1f000
	s_mov_b32 s62, 0x20000
	s_mov_b32 s63, 0x21000
	s_mov_b32 s64, 0x22000
	s_mov_b32 s65, 0x23000
	s_mov_b32 s66, 0x24000
	s_mov_b32 s67, 0x25000
	s_mov_b32 s70, 0x26000
	s_mov_b32 s71, 0x27000
	s_mov_b32 s72, 0x28000
	s_mov_b32 s73, 0x29000
	s_mov_b32 s74, 0x2a000
	s_mov_b32 s75, 0x2b000
	s_mov_b32 s76, 0x2c000
	s_mov_b32 s77, 0x2d000
	s_mov_b32 s78, 0x2e000
	s_mov_b32 s79, 0x2f000
	s_mov_b32 s80, 0x30000
	s_mov_b32 s81, 0x31000
	s_mov_b32 s82, 0x32000
	s_mov_b32 s83, 0x33000
	s_mov_b32 s84, 0x34000
	s_mov_b32 s85, 0x35000
	s_mov_b32 s86, 0x36000
	s_mov_b32 s87, 0x37000
	v_lshlrev_b32_e32 v92, 2, v0
	s_mov_b32 s88, 0x3f2aaaab
	v_mov_b32_e32 v123, 0x3ecc95a3
	s_mov_b32 s89, 0x3f317218
	s_mov_b32 s90, 0x7f800000
	s_mov_b32 s91, 0x33800000
	s_movk_i32 s92, 0x90
	s_mov_b32 s93, 0xf800000
	v_mov_b32_e32 v124, 0x260
	s_mov_b64 s[20:21], 0x4000
	v_mov_b32_e32 v125, 0xe00
	v_mov_b32_e32 v126, 0x7f800000
	v_mov_b32_e32 v127, 0x7fc00000
	v_mov_b32_e32 v128, 0xff800000

.Lrm_done_attn_34116:
	s_mov_b64 s[26:27], s[0:1]
	s_barrier
	s_load_dwordx2 s[86:87], s[0:1], 0xe0
	v_readfirstlane_b32 s8, v0
	s_cmpk_gt_i32 s3, 0x1ff
	s_cbranch_scc1 .LBB0_1071
	v_mbcnt_hi_u32_b32 v10, -1, v216
	v_and_b32_e32 v12, 64, v10
	v_xor_b32_e32 v11, 16, v10
	v_add_u32_e32 v12, 64, v12
	v_cmp_lt_i32_e32 vcc, v11, v12
	v_and_b32_e32 v1, 7, v0
	v_add_u32_e32 v6, 0x400, v0
	v_cndmask_b32_e32 v11, v10, v11, vcc
	s_ashr_i32 s28, s8, 6
	v_lshl_add_u32 v3, v1, 4, 0
	s_movk_i32 s8, 0x1070
	v_add_u32_e32 v5, 0x200, v0
	v_ashrrev_i32_e32 v90, 3, v6
	v_add_u32_e32 v6, 0x600, v0
	v_lshlrev_b32_e32 v111, 2, v11
	v_xor_b32_e32 v11, 32, v10
	v_mad_u32_u24 v4, v1, s8, v3
	v_ashrrev_i32_e32 v86, 3, v0
	v_ashrrev_i32_e32 v88, 3, v5
	v_ashrrev_i32_e32 v92, 3, v6
	v_bfe_u32 v6, v0, 4, 2
	v_cmp_lt_i32_e32 vcc, v11, v12
	v_lshl_add_u32 v85, v86, 1, v4
	v_lshl_add_u32 v108, v88, 1, v4
	v_lshl_add_u32 v109, v90, 1, v4
	v_lshl_add_u32 v110, v92, 1, v4
	v_lshlrev_b32_e32 v4, 3, v6
	v_lshlrev_b32_e32 v6, 2, v6
	v_cndmask_b32_e32 v10, v10, v11, vcc
	s_and_b32 s43, s28, 3
	s_lshl_b32 s16, s28, 4
	v_and_b32_e32 v9, 15, v0
	v_lshlrev_b32_e32 v112, 2, v10
	v_or_b32_e32 v10, 2, v6
	s_lshr_b32 s28, s28, 2
	v_cmp_gt_u32_e64 s[20:21], v10, v9
	v_or_b32_e32 v10, 3, v6
	s_lshl_b32 s31, s28, 7
	v_cmp_gt_u32_e64 s[22:23], v10, v9
	v_and_or_b32 v10, v0, 63, 48
	s_movk_i32 s34, 0x210
	v_mov_b32_e32 v11, s31
	v_mad_u32_u24 v10, v10, s34, v11
	v_add3_u32 v10, v10, v4, 0
	v_add_u32_e32 v113, 0x9000, v10
	v_mad_u32_u24 v10, v9, s34, v11
	v_add3_u32 v10, v10, v4, 0
	s_lshl_b32 s44, s28, 6
	s_mulk_i32 s28, 0x2400
	s_movk_i32 s30, 0x90
	s_andn2_b32 s16, s16, 63
	v_add_u32_e32 v114, 0x9000, v10
	v_mov_b32_e32 v10, s28
	v_lshlrev_b32_e32 v84, 3, v1
	s_movk_i32 s14, 0x7f
	v_mul_lo_u32 v1, v86, s30
	v_mul_lo_u32 v5, v88, s30
	v_mul_lo_u32 v7, v90, s30
	v_mul_lo_u32 v8, v92, s30
	s_ashr_i32 s17, s16, 31
	v_mad_u32_u24 v10, v9, s30, v10
	v_and_b32_e32 v0, 48, v0
	s_mov_b32 s29, 0
	v_mov_b32_e32 v2, 0
	v_cmp_lt_i32_e64 s[8:9], s14, v86
	v_ashrrev_i32_e32 v87, 31, v86
	v_cmp_lt_i32_e64 s[10:11], s14, v88
	v_ashrrev_i32_e32 v89, 31, v88
	v_cmp_lt_i32_e64 s[12:13], s14, v90
	v_ashrrev_i32_e32 v91, 31, v90
	v_cmp_lt_i32_e64 s[14:15], s14, v92
	v_ashrrev_i32_e32 v93, 31, v92
	v_or_b32_e32 v94, s16, v9
	v_mov_b32_e32 v95, s17
	v_cmp_gt_u32_e64 s[16:17], v6, v9
	v_cmp_lt_u32_e64 s[18:19], v6, v9
	v_add3_u32 v115, v10, v0, 0
	v_or_b32_e32 v116, s44, v9
	v_mov_b64_e32 v[96:97], s[26:27]
	s_and_b32 s30, s2, 7
	s_lshl_b32 s30, s30, 23
	s_add_u32 s30, s30, 0xd000000
	s_mov_b32 s31, 0
	s_movk_i32 s45, 0xe00
	v_add_u32_e32 v117, v3, v1
	v_add_u32_e32 v118, v3, v5
	v_add_u32_e32 v119, v3, v7
	v_add_u32_e32 v120, v3, v8
	v_lshlrev_b32_e32 v98, 1, v4
	s_mov_b32 s48, 0xf149f2ca
	v_lshlrev_b32_e32 v100, 1, v6
	s_mov_b64 s[34:35], 0x9000200
	s_mov_b32 s49, 0x9000000
	v_mov_b32_e32 v121, 0xf149f2ca

.LBB0_1071:
	v_mov_b32_e32 v54, v176
	s_cmp_eq_u32 s68, 0x100
	s_cbranch_scc0 .Lrm_orig_conf_34981
	s_and_b32 s29, s2, 7
	s_lshl_b32 s29, s29, 7
	s_lshr_b32 s98, s2, 3
	s_add_i32 s29, s29, s98
	s_add_i32 s99, s29, 96
	s_mov_b32 s3, 32
	s_branch .Lrm_done_conf_34981
.Lrm_orig_conf_34981:
	s_mov_b32 s29, s2
	s_mov_b32 s3, s68
	s_movk_i32 s99, 0x3ff
.Lrm_done_conf_34981:
	s_mov_b64 s[8:9], s[0:1]
	v_readfirstlane_b32 s20, v54
	s_cmpk_gt_i32 s29, 0x3ff
	s_cbranch_scc1 .LBB0_1104
	v_mov_b64_e32 v[10:11], s[8:9]
	flat_load_dwordx4 v[2:5], v[10:11] offset:120
	flat_load_dwordx4 v[6:9], v[10:11] offset:136
	flat_load_dwordx2 v[40:41], v[10:11] offset:216
	flat_load_dwordx2 v[12:13], v[10:11] offset:152
	v_and_b32_e32 v55, 0xff, v54
	v_mov_b32_e32 v0, 0
	v_lshlrev_b32_e32 v10, 2, v55
	v_mov_b32_e32 v11, v0
	s_movk_i32 s10, 0x7000
	s_mov_b32 s11, 0x8000
	s_mov_b32 s12, 0x9000
	s_mov_b32 s13, 0xa000
	s_mov_b32 s14, 0xb000
	s_mov_b32 s15, 0xc000
	s_mov_b32 s16, 0xd000
	s_mov_b32 s17, 0xe000
	s_mov_b64 s[8:9], 0x7c00
	s_mov_b32 s18, 0xf000
	v_and_b32_e32 v56, 63, v54
	s_lshl_b32 s22, s29, 5
	v_ashrrev_i32_e32 v90, 5, v54
	v_lshlrev_b32_e32 v57, 3, v54
	v_and_b32_e32 v94, 0xf8, v57
	v_mov_b32_e32 v1, v0
	v_lshlrev_b32_e32 v52, 1, v94
	s_waitcnt vmcnt(0) lgkmcnt(0)
	v_lshl_add_u64 v[2:3], v[2:3], 0, v[10:11]
	v_add_co_u32_e32 v16, vcc, s10, v2
	v_lshl_add_u64 v[14:15], v[2:3], 0, s[8:9]
	s_nop 0
	v_addc_co_u32_e32 v17, vcc, 0, v3, vcc
	v_add_co_u32_e32 v18, vcc, s11, v2
	s_movk_i32 s8, 0x1000
	s_nop 0
	v_addc_co_u32_e32 v19, vcc, 0, v3, vcc
	v_add_co_u32_e32 v20, vcc, s12, v2
	s_nop 1
	v_addc_co_u32_e32 v21, vcc, 0, v3, vcc
	v_add_co_u32_e32 v22, vcc, s13, v2
	s_nop 1
	v_addc_co_u32_e32 v23, vcc, 0, v3, vcc
	v_add_co_u32_e32 v24, vcc, s14, v2
	s_nop 1
	v_addc_co_u32_e32 v25, vcc, 0, v3, vcc
	v_add_co_u32_e32 v26, vcc, s15, v2
	s_nop 1
	v_addc_co_u32_e32 v27, vcc, 0, v3, vcc
	v_add_co_u32_e32 v28, vcc, s16, v2
	s_nop 1
	v_addc_co_u32_e32 v29, vcc, 0, v3, vcc
	v_add_co_u32_e32 v30, vcc, s17, v2
	s_nop 1
	v_addc_co_u32_e32 v31, vcc, 0, v3, vcc
	v_add_co_u32_e32 v2, vcc, s18, v2
	s_nop 1
	v_addc_co_u32_e32 v3, vcc, 0, v3, vcc
	global_load_dword v58, v[16:17], off offset:3072
	global_load_dword v59, v[14:15], off offset:1024
	global_load_dword v60, v[14:15], off offset:2048
	global_load_dword v61, v[18:19], off offset:3072
	global_load_dword v62, v[20:21], off offset:1024
	global_load_dword v63, v[20:21], off offset:2048
	global_load_dword v64, v[20:21], off offset:3072
	global_load_dword v65, v[14:15], off offset:3072
	global_load_dword v66, v[22:23], off offset:-4096
	global_load_dword v67, v[22:23], off
	global_load_dword v68, v[22:23], off offset:1024
	global_load_dword v69, v[22:23], off offset:2048
	global_load_dword v70, v[22:23], off offset:3072
	global_load_dword v71, v[26:27], off offset:-4096
	global_load_dword v72, v[26:27], off
	global_load_dword v73, v[26:27], off offset:1024
	global_load_dword v74, v[26:27], off offset:2048
	global_load_dword v75, v[26:27], off offset:3072
	global_load_dword v76, v[30:31], off offset:-4096
	global_load_dword v77, v[30:31], off
	global_load_dword v78, v[30:31], off offset:1024
	global_load_dword v79, v[30:31], off offset:2048
	global_load_dword v80, v[30:31], off offset:3072
	global_load_dword v81, v[24:25], off offset:1024
	global_load_dword v82, v[24:25], off offset:2048
	global_load_dword v83, v[24:25], off offset:3072
	global_load_dword v84, v[28:29], off offset:1024
	global_load_dword v85, v[28:29], off offset:2048
	global_load_dword v86, v[28:29], off offset:3072
	global_load_dword v87, v[2:3], off
	global_load_dword v88, v[2:3], off offset:1024
	v_lshl_add_u64 v[2:3], v[4:5], 0, v[10:11]
	global_load_dword v89, v[2:3], off offset:1024
	v_lshlrev_b32_e32 v2, 4, v56
	v_mov_b32_e32 v3, v0
	v_lshl_add_u64 v[4:5], v[6:7], 0, v[2:3]
	v_lshl_add_u64 v[8:9], v[8:9], 0, v[2:3]
	v_lshl_add_u64 v[2:3], v[12:13], 0, v[2:3]
	v_add_co_u32_e32 v2, vcc, s8, v2
	global_load_dwordx4 v[4:7], v[4:5], off offset:1024
	s_nop 0
	v_addc_co_u32_e32 v3, vcc, 0, v3, vcc
	global_load_dwordx4 v[8:11], v[8:9], off offset:1024
	s_and_b32 s8, s2, 7
	s_lshl_b32 s8, s8, 23
	s_add_u32 s8, s8, 0xd000000
	s_mov_b32 s9, 0
	global_load_dwordx4 v[12:15], v[2:3], off offset:3072
	v_lshl_add_u64 v[50:51], v[40:41], 0, s[8:9]
	s_ashr_i32 s8, s29, 7
	s_and_b32 s9, s22, 0xfe0
	s_sub_i32 s18, s9, 30
	s_ashr_i32 s9, s8, 31
	s_lshl_b64 s[16:17], s[8:9], 12
	v_add_u32_e32 v24, s18, v90
	s_movk_i32 s8, 0x7c0
	v_mov_b32_e32 v2, v0
	v_mov_b32_e32 v3, v0
	v_cmp_gt_i32_e64 s[8:9], s8, v54
	v_cmp_lt_i32_e32 vcc, -1, v24
	v_mov_b64_e32 v[22:23], v[2:3]
	v_mov_b64_e32 v[18:19], v[2:3]
	s_and_b64 s[12:13], s[8:9], vcc
	v_mov_b64_e32 v[20:21], v[0:1]
	v_mov_b64_e32 v[16:17], v[0:1]
	s_and_saveexec_b64 s[10:11], s[12:13]
	s_cbranch_execz .LBB0_1074
	v_mov_b32_e32 v25, v0
	v_lshl_add_u64 v[16:17], s[16:17], 0, v[24:25]
	s_movk_i32 s14, 0xe00
	v_mad_u64_u32 v[18:19], s[12:13], v16, s14, v[50:51]
	v_mad_i32_i24 v19, v17, s14, v19
	v_mov_b32_e32 v53, v0
	v_lshl_add_u64 v[24:25], v[18:19], 0, v[52:53]
	global_load_dwordx4 v[16:19], v[24:25], off offset:2560
	global_load_dwordx4 v[20:23], v[24:25], off offset:3072

.LBB0_1148:
	s_or_b64 exec, exec, s[48:49]
	s_waitcnt vmcnt(0)
	v_mov_b32_e32 v0, v176
	s_cmp_eq_u32 s68, 0x100
	s_cbranch_scc0 .Lrm_orig_mix2_36721
	s_and_b32 s3, s2, 7
	s_lshl_b32 s3, s3, 6
	s_lshr_b32 s98, s2, 3
	s_add_i32 s3, s3, s98
	s_add_i32 s99, s3, 32
	s_mov_b32 s22, 32
	s_branch .Lrm_done_mix2_36721
.Lrm_orig_mix2_36721:
	s_mov_b32 s3, s2
	s_mov_b32 s22, s68
	s_movk_i32 s99, 0x1ff
.Lrm_done_mix2_36721:
	s_waitcnt lgkmcnt(0)
	s_barrier
	s_mov_b64 s[8:9], s[0:1]
	v_readfirstlane_b32 s10, v0
	s_cmpk_lt_i32 s3, 0x200
	s_cbranch_scc0 .LBB0_1182
	s_ashr_i32 s23, s10, 6
	v_and_b32_e32 v0, 63, v0
	s_lshl_b32 s10, s23, 10
	v_mov_b32_e32 v75, 0
	s_add_i32 s10, s10, 0
	v_lshlrev_b32_e32 v1, 4, v0
	v_lshlrev_b32_e32 v2, 1, v0
	s_lshl_b32 s26, s23, 3
	v_lshlrev_b32_e32 v4, 3, v0
	v_lshlrev_b32_e32 v72, 2, v0
	v_lshlrev_b32_e32 v76, 5, v0
	v_mov_b32_e32 v77, v75
	v_add_u32_e32 v73, s10, v1
	v_add_u32_e32 v108, 0, v1
	s_ashr_i32 s27, s26, 31
	v_mov_b64_e32 v[78:79], s[8:9]
	s_mov_b64 s[10:11], 0x1a000000
	s_mov_b64 s[12:13], 0x9000000
	v_lshlrev_b32_e32 v74, 4, v0
	s_movk_i32 s28, 0x1000
	v_lshlrev_b32_e32 v80, 4, v2
	s_mov_b64 s[14:15], 0x1400
	s_mov_b64 s[16:17], 0x18000000
	s_and_b32 s29, s2, 7
	s_lshl_b32 s29, s29, 23
	s_add_u32 s29, s29, 0xd000000
	v_lshlrev_b32_e32 v82, 1, v4
	s_and_b32 s30, s2, 7
	s_lshl_b32 s30, s30, 23
	s_add_u32 s30, s30, 0xd001000
	s_and_b32 s31, s2, 7
	s_lshl_b32 s31, s31, 23
	s_add_u32 s31, s31, 0xd002000
	s_and_b32 s34, s2, 7
	s_lshl_b32 s34, s34, 23
	s_add_u32 s34, s34, 0xd003000
	s_and_b32 s35, s2, 7
	s_lshl_b32 s35, s35, 23
	s_add_u32 s35, s35, 0xd004000
	s_and_b32 s36, s2, 7
	s_lshl_b32 s36, s36, 23
	s_add_u32 s36, s36, 0xd005000
	s_and_b32 s37, s2, 7
	s_lshl_b32 s37, s37, 23
	s_add_u32 s37, s37, 0xd006000
	v_mov_b32_e32 v109, 0x358637bd
	s_mov_b32 s38, 0x800000
	s_movk_i32 s39, 0x2000
	s_movk_i32 s40, 0x3000
	v_mov_b32_e32 v110, 0xe00
	s_branch .LBB0_1152
